# baseline (speedup 1.0000x reference)
; #define SBAR() __builtin_amdgcn_sched_barrier(0)
; #define KRD(dst, addr, off) asm volatile("ds_read_b128 %0, %1 offset:%2" : "=&v"(dst) : "v"(addr), "i"(off) : "memory")
; template <int MODE>
; __device__ __forceinline__ void qkt(f32x16& p0, f32x16& p1, const int (&ka)[4], const int (&kra)[4], const bf16x8* qr) {
;     ...
;     if constexpr (MODE == 0) {
;         KRD(kb0[0], ka[0], 0); KRD(kb1[0], ka[0], 8192); KRD(kb0[1], ka[1], 0); KRD(kb1[1], ka[1], 8192);
;         KRD(kb0[2], ka[2], 0); KRD(kb1[2], ka[2], 8192); asm volatile("s_waitcnt lgkmcnt(4)" ::: "memory"); SBAR(); p0 = __builtin_amdgcn_mfma_f32_32x32x16_bf16(kb0[0], qr[0], zz, 0, 0, 0); p1 = __builtin_amdgcn_mfma_f32_32x32x16_bf16(kb1[0], qr[0], zz, 0, 0, 0);
;         KRD(kb0[0], ka[3], 0); KRD(kb1[0], ka[3], 8192); asm volatile("s_waitcnt lgkmcnt(4)" ::: "memory"); SBAR(); p0 = __builtin_amdgcn_mfma_f32_32x32x16_bf16(kb0[1], qr[1], p0, 0, 0, 0); p1 = __builtin_amdgcn_mfma_f32_32x32x16_bf16(kb1[1], qr[1], p1, 0, 0, 0);
;         KRD(kb0[1], ka[0], 128); KRD(kb1[1], ka[0], 8320); asm volatile("s_waitcnt lgkmcnt(4)" ::: "memory"); SBAR(); p0 = __builtin_amdgcn_mfma_f32_32x32x16_bf16(kb0[2], qr[2], p0, 0, 0, 0); p1 = __builtin_amdgcn_mfma_f32_32x32x16_bf16(kb1[2], qr[2], p1, 0, 0, 0);
;         KRD(kb0[2], ka[1], 128); KRD(kb1[2], ka[1], 8320); asm volatile("s_waitcnt lgkmcnt(4)" ::: "memory"); SBAR(); p0 = __builtin_amdgcn_mfma_f32_32x32x16_bf16(kb0[0], qr[3], p0, 0, 0, 0); p1 = __builtin_amdgcn_mfma_f32_32x32x16_bf16(kb1[0], qr[3], p1, 0, 0, 0);
;         KRD(kb0[0], ka[2], 128); KRD(kb1[0], ka[2], 8320); asm volatile("s_waitcnt lgkmcnt(4)" ::: "memory"); SBAR(); p0 = __builtin_amdgcn_mfma_f32_32x32x16_bf16(kb0[1], qr[4], p0, 0, 0, 0); p1 = __builtin_amdgcn_mfma_f32_32x32x16_bf16(kb1[1], qr[4], p1, 0, 0, 0);
;         KRD(kb0[1], ka[3], 128); KRD(kb1[1], ka[3], 8320); asm volatile("s_waitcnt lgkmcnt(4)" ::: "memory"); SBAR(); p0 = __builtin_amdgcn_mfma_f32_32x32x16_bf16(kb0[2], qr[5], p0, 0, 0, 0); p1 = __builtin_amdgcn_mfma_f32_32x32x16_bf16(kb1[2], qr[5], p1, 0, 0, 0);
;         KRD(kb0[2], kra[0], 0); KRD(kb1[2], kra[0], 4096); asm volatile("s_waitcnt lgkmcnt(4)" ::: "memory"); SBAR(); p0 = __builtin_amdgcn_mfma_f32_32x32x16_bf16(kb0[0], qr[6], p0, 0, 0, 0); p1 = __builtin_amdgcn_mfma_f32_32x32x16_bf16(kb1[0], qr[6], p1, 0, 0, 0);
.LBB0_286:
	s_setprio 1
	s_waitcnt lgkmcnt(6)
	v_mfma_f32_32x32x16_bf16 v[80:95], v[192:195], v[96:99], 0
	ds_read_b128 v[192:195], v248 offset:0x80
	v_mfma_f32_32x32x16_bf16 v[64:79], v[196:199], v[96:99], 0
	ds_read_b128 v[196:199], v248 offset:0x2080
	s_waitcnt lgkmcnt(6)
	v_mfma_f32_32x32x16_bf16 v[80:95], v[224:227], v[100:103], v[80:95]
	ds_read_b128 v[224:227], v250 offset:0x80
	v_mfma_f32_32x32x16_bf16 v[64:79], v[228:231], v[100:103], v[64:79]
	ds_read_b128 v[228:231], v250 offset:0x2080
	s_waitcnt lgkmcnt(6)
	v_mfma_f32_32x32x16_bf16 v[80:95], v[232:235], v[104:107], v[80:95]
	ds_read_b128 v[232:235], v252 offset:0x80
	v_mfma_f32_32x32x16_bf16 v[64:79], v[236:239], v[104:107], v[64:79]
	ds_read_b128 v[236:239], v252 offset:0x2080
	s_waitcnt lgkmcnt(6)
	v_mfma_f32_32x32x16_bf16 v[80:95], v[240:243], v[108:111], v[80:95]
	ds_read_b128 v[240:243], v188 offset:0x80
	v_mfma_f32_32x32x16_bf16 v[64:79], v[244:247], v[108:111], v[64:79]
	ds_read_b128 v[244:247], v188 offset:0x2080
	s_waitcnt lgkmcnt(6)
	v_mfma_f32_32x32x16_bf16 v[80:95], v[192:195], v[112:115], v[80:95]
	ds_read_b128 v[192:195], v249 offset:0x0
	v_mfma_f32_32x32x16_bf16 v[64:79], v[196:199], v[112:115], v[64:79]
	ds_read_b128 v[196:199], v249 offset:0x1000
	s_waitcnt lgkmcnt(6)
	v_mfma_f32_32x32x16_bf16 v[80:95], v[224:227], v[116:119], v[80:95]
	ds_read_b128 v[224:227], v251 offset:0x0
	v_mfma_f32_32x32x16_bf16 v[64:79], v[228:231], v[116:119], v[64:79]
	ds_read_b128 v[228:231], v251 offset:0x1000
	s_waitcnt lgkmcnt(6)
	v_mfma_f32_32x32x16_bf16 v[80:95], v[232:235], v[120:123], v[80:95]
	ds_read_b128 v[232:235], v253 offset:0x0
	v_mfma_f32_32x32x16_bf16 v[64:79], v[236:239], v[120:123], v[64:79]
	ds_read_b128 v[236:239], v253 offset:0x1000
	s_waitcnt lgkmcnt(6)
	v_mfma_f32_32x32x16_bf16 v[80:95], v[240:243], v[124:127], v[80:95]
	ds_read_b128 v[240:243], v191 offset:0x0
	v_mfma_f32_32x32x16_bf16 v[64:79], v[244:247], v[124:127], v[64:79]
	ds_read_b128 v[244:247], v191 offset:0x1000
	v_lshl_add_u32 v200, s44, 14, v212
	s_waitcnt lgkmcnt(6)
	v_mfma_f32_32x32x16_bf16 v[80:95], v[192:195], v[128:131], v[80:95]
	ds_read_b64_tr_b16 v[192:193], v200 offset:0x0
	ds_read_b64_tr_b16 v[194:195], v200 offset:0x800
	v_mfma_f32_32x32x16_bf16 v[64:79], v[196:199], v[128:131], v[64:79]
	ds_read_b64_tr_b16 v[196:197], v200 offset:0x1000
	ds_read_b64_tr_b16 v[198:199], v200 offset:0x1800
	s_waitcnt lgkmcnt(8)
	v_mfma_f32_32x32x16_bf16 v[80:95], v[224:227], v[136:139], v[80:95]
	ds_read_b64_tr_b16 v[224:225], v200 offset:0x2000
	ds_read_b64_tr_b16 v[226:227], v200 offset:0x2800
	v_mfma_f32_32x32x16_bf16 v[64:79], v[228:231], v[136:139], v[64:79]
	ds_read_b64_tr_b16 v[228:229], v200 offset:0x3000
	ds_read_b64_tr_b16 v[230:231], v200 offset:0x3800
	s_waitcnt lgkmcnt(10)
	v_mfma_f32_32x32x16_bf16 v[80:95], v[232:235], v[132:135], v[80:95]
	ds_read_b64_tr_b16 v[232:233], v200 offset:0x200
	ds_read_b64_tr_b16 v[234:235], v200 offset:0xa00
	v_mfma_f32_32x32x16_bf16 v[64:79], v[236:239], v[132:135], v[64:79]
	ds_read_b64_tr_b16 v[236:237], v200 offset:0x1200
	ds_read_b64_tr_b16 v[238:239], v200 offset:0x1a00
	s_waitcnt lgkmcnt(12)
	v_mfma_f32_32x32x16_bf16 v[80:95], v[240:243], v[140:143], v[80:95]
	ds_read_b64_tr_b16 v[240:241], v200 offset:0x2200
	ds_read_b64_tr_b16 v[242:243], v200 offset:0x2a00
	v_mfma_f32_32x32x16_bf16 v[64:79], v[244:247], v[140:143], v[64:79]
	s_waitcnt lgkmcnt(12)
	v_mfma_f32_32x32x16_bf16 v[0:15], v[164:167], v[192:195], v[0:15]
	ds_read_b64_tr_b16 v[244:245], v200 offset:0x3200
	ds_read_b64_tr_b16 v[246:247], v200 offset:0x3a00
	s_waitcnt lgkmcnt(12)
	v_mfma_f32_32x32x16_bf16 v[0:15], v[168:171], v[196:199], v[0:15]
	ds_read_b64_tr_b16 v[192:193], v200 offset:0x400
	ds_read_b64_tr_b16 v[194:195], v200 offset:0xc00
	s_waitcnt lgkmcnt(12)
	v_mfma_f32_32x32x16_bf16 v[0:15], v[172:175], v[224:227], v[0:15]
	ds_read_b64_tr_b16 v[196:197], v200 offset:0x1400
	ds_read_b64_tr_b16 v[198:199], v200 offset:0x1c00
	s_waitcnt lgkmcnt(12)
	v_mfma_f32_32x32x16_bf16 v[0:15], v[176:179], v[228:231], v[0:15]
	ds_read_b64_tr_b16 v[224:225], v200 offset:0x2400
	ds_read_b64_tr_b16 v[226:227], v200 offset:0x2c00
	s_waitcnt lgkmcnt(12)
	v_mfma_f32_32x32x16_bf16 v[48:63], v[164:167], v[232:235], v[48:63]
	ds_read_b64_tr_b16 v[228:229], v200 offset:0x3400
	ds_read_b64_tr_b16 v[230:231], v200 offset:0x3c00
	s_waitcnt lgkmcnt(12)
	v_mfma_f32_32x32x16_bf16 v[48:63], v[168:171], v[236:239], v[48:63]
	ds_read_b64_tr_b16 v[232:233], v200 offset:0x600
	ds_read_b64_tr_b16 v[234:235], v200 offset:0xe00
	v_max_f32_e32 v248, v81, v81
	v_max_f32_e32 v250, v80, v80
	v_max_f32_e32 v248, v250, v248
	s_waitcnt lgkmcnt(12)
	v_mfma_f32_32x32x16_bf16 v[48:63], v[172:175], v[240:243], v[48:63]
	ds_read_b64_tr_b16 v[236:237], v200 offset:0x1600
	ds_read_b64_tr_b16 v[238:239], v200 offset:0x1e00
	v_max3_f32 v248, v248, v82, v83
	v_max3_f32 v248, v248, v84, v85
	v_max3_f32 v248, v248, v86, v87
	s_waitcnt lgkmcnt(12)
	v_mfma_f32_32x32x16_bf16 v[48:63], v[176:179], v[244:247], v[48:63]
	ds_read_b64_tr_b16 v[240:241], v200 offset:0x2600
	ds_read_b64_tr_b16 v[242:243], v200 offset:0x2e00
	v_max3_f32 v248, v248, v88, v89
	v_max3_f32 v248, v248, v90, v91
	v_max3_f32 v248, v248, v92, v93
	s_waitcnt lgkmcnt(12)
	v_mfma_f32_32x32x16_bf16 v[32:47], v[164:167], v[192:195], v[32:47]
	ds_read_b64_tr_b16 v[244:245], v200 offset:0x3600
	ds_read_b64_tr_b16 v[246:247], v200 offset:0x3e00
	v_max3_f32 v248, v248, v94, v95
	v_max3_f32 v248, v248, v64, v65
	v_max3_f32 v248, v248, v66, v67
	s_waitcnt lgkmcnt(12)
	v_mfma_f32_32x32x16_bf16 v[32:47], v[168:171], v[196:199], v[32:47]
	v_max3_f32 v248, v248, v68, v69
	v_max3_f32 v248, v248, v70, v71
	v_max3_f32 v248, v248, v72, v73
	s_waitcnt lgkmcnt(10)
	v_mfma_f32_32x32x16_bf16 v[32:47], v[172:175], v[224:227], v[32:47]
	v_max3_f32 v248, v248, v74, v75
	v_max3_f32 v248, v248, v76, v77
	v_max3_f32 v248, v248, v78, v79
	s_waitcnt lgkmcnt(8)
	v_mfma_f32_32x32x16_bf16 v[32:47], v[176:179], v[228:231], v[32:47]
	s_waitcnt lgkmcnt(6)
	v_mfma_f32_32x32x16_bf16 v[16:31], v[164:167], v[232:235], v[16:31]
	s_waitcnt lgkmcnt(4)
	v_mfma_f32_32x32x16_bf16 v[16:31], v[168:171], v[236:239], v[16:31]
	v_mov_b32_e32 v164, v248
	v_mov_b32_e32 v165, v248
	s_nop 1
	v_permlane32_swap_b32_e32 v164, v165
	v_max_f32_e32 v165, v165, v165
	v_max_f32_e32 v164, v164, v164
	s_waitcnt lgkmcnt(2)
	v_mfma_f32_32x32x16_bf16 v[16:31], v[172:175], v[240:243], v[16:31]
	v_max_f32_e32 v164, v164, v165
	v_sub_f32_e32 v165, v164, v221
	v_cmp_ge_f32_e32 vcc, s1, v165
	v_max_f32_e32 v165, v221, v221
	v_max_f32_e32 v164, v165, v164
	v_sub_f32_e32 v165, v221, v164
	s_waitcnt lgkmcnt(0)
	v_mfma_f32_32x32x16_bf16 v[16:31], v[176:179], v[244:247], v[16:31]
	v_mul_f32_e32 v165, 0x3dd53b94, v165
	v_exp_f32_e32 v165, v165
	s_cmp_eq_u64 vcc, exec
	s_cselect_b64 s[8:9], -1, 0
	v_cndmask_b32_e64 v224, v165, 1.0, s[8:9]
	v_cmp_gt_f32_e32 vcc, 1.0, v224
	s_setprio 0
	s_barrier
; #define RESC(a) do { if (__any((a) < 1.f)) { if (hi == 0) al_l[r32] = (a); asm volatile("s_waitcnt lgkmcnt(0)" ::: "memory"); \
;     _Pragma("unroll") for (int d = 0; d < 4; ++d) _Pragma("unroll") for (int r = 0; r < 16; ++r) o[d][r] *= al_l[crow(r, hi)]; } } while (0)
; template <int MODE> ...
;     ...
;         if (ACT(j)) { partialSM<MODE>(p0, p1, m_reg, mn, al, REL0(j), hi, NEEDM(j)); RESC(al); finishSM(p0, p1, al, l_reg, pa0, pa1, pa2, pa3); }
	s_cbranch_vccz .LBB0_290
	s_and_saveexec_b64 s[4:5], s[6:7]
	ds_write_b32 v222, v224 offset:128
	s_or_b64 exec, exec, s[4:5]
	s_waitcnt lgkmcnt(0)
	v_add_u32_e32 v165, s23, v211
	ds_read_b128 v[166:169], v165 offset:224
	ds_read_b128 v[170:173], v165 offset:192
	ds_read_b128 v[174:177], v165 offset:160
	ds_read_b128 v[226:229], v165 offset:128
	s_waitcnt lgkmcnt(3)
	v_pk_mul_f32 v[12:13], v[12:13], v[166:167]
	s_waitcnt lgkmcnt(2)
	v_pk_mul_f32 v[8:9], v[8:9], v[170:171]
	s_waitcnt lgkmcnt(1)
	v_pk_mul_f32 v[4:5], v[4:5], v[174:175]
	v_pk_mul_f32 v[14:15], v[14:15], v[168:169]
	v_pk_mul_f32 v[10:11], v[10:11], v[172:173]
	v_pk_mul_f32 v[6:7], v[6:7], v[176:177]
	s_waitcnt lgkmcnt(0)
	v_pk_mul_f32 v[2:3], v[2:3], v[228:229]
	v_pk_mul_f32 v[0:1], v[0:1], v[226:227]
	v_pk_mul_f32 v[60:61], v[60:61], v[166:167]
	v_pk_mul_f32 v[56:57], v[56:57], v[170:171]
	v_pk_mul_f32 v[52:53], v[52:53], v[174:175]
	v_pk_mul_f32 v[62:63], v[62:63], v[168:169]
	v_pk_mul_f32 v[58:59], v[58:59], v[172:173]
	v_pk_mul_f32 v[54:55], v[54:55], v[176:177]
	v_pk_mul_f32 v[50:51], v[50:51], v[228:229]
	v_pk_mul_f32 v[48:49], v[48:49], v[226:227]
	v_pk_mul_f32 v[44:45], v[44:45], v[166:167]
	v_pk_mul_f32 v[40:41], v[40:41], v[170:171]
	v_pk_mul_f32 v[36:37], v[36:37], v[174:175]
	v_pk_mul_f32 v[46:47], v[46:47], v[168:169]
	v_pk_mul_f32 v[42:43], v[42:43], v[172:173]
	v_pk_mul_f32 v[38:39], v[38:39], v[176:177]
	v_pk_mul_f32 v[34:35], v[34:35], v[228:229]
	v_pk_mul_f32 v[32:33], v[32:33], v[226:227]
	v_pk_mul_f32 v[28:29], v[28:29], v[166:167]
	v_pk_mul_f32 v[24:25], v[24:25], v[170:171]
	v_pk_mul_f32 v[20:21], v[20:21], v[174:175]
	v_pk_mul_f32 v[30:31], v[30:31], v[168:169]
	v_pk_mul_f32 v[26:27], v[26:27], v[172:173]
	v_pk_mul_f32 v[22:23], v[22:23], v[176:177]
	v_pk_mul_f32 v[18:19], v[18:19], v[228:229]
	v_pk_mul_f32 v[16:17], v[16:17], v[226:227]
